# merge phase: the K=512 projection GEMM loops also run a 3-stage LDS ring (two k-steps of loads in flight) like the gate GEMM
# speedup vs baseline: 1.0381x; 1.0097x over previous
.LBB0_736:
	s_nop 5
	v_mul_f32_e32 v0, 0xbfb8aa3b, v0
	v_exp_f32_e32 v0, v0
	v_mul_f32_e32 v1, 0xbfb8aa3b, v1
	v_exp_f32_e32 v1, v1
	v_mul_f32_e32 v20, 0xbfb8aa3b, v20
	v_add_f32_e32 v0, 1.0, v0
	v_rcp_f32_e32 v204, v0
	v_add_f32_e32 v0, 1.0, v1
	v_mul_f32_e32 v1, 0xbfb8aa3b, v2
	v_exp_f32_e32 v1, v1
	v_mul_f32_e32 v2, 0xbfb8aa3b, v3
	v_exp_f32_e32 v2, v2
	v_exp_f32_e32 v20, v20
	v_mul_f32_e32 v21, 0xbfb8aa3b, v21
	v_exp_f32_e32 v21, v21
	v_rcp_f32_e32 v205, v0
	v_add_f32_e32 v0, 1.0, v1
	v_mul_f32_e32 v1, 0xbfb8aa3b, v8
	v_rcp_f32_e32 v192, v0
	v_add_f32_e32 v0, 1.0, v2
	v_exp_f32_e32 v1, v1
	v_mul_f32_e32 v2, 0xbfb8aa3b, v9
	v_exp_f32_e32 v2, v2
	v_add_f32_e32 v20, 1.0, v20
	v_mul_f32_e32 v4, 0xbfb8aa3b, v4
	v_mul_f32_e32 v24, 0xbfb8aa3b, v24
	v_rcp_f32_e32 v189, v20
	v_add_f32_e32 v20, 1.0, v21
	v_mul_f32_e32 v21, 0xbfb8aa3b, v22
	v_exp_f32_e32 v4, v4
	v_mul_f32_e32 v5, 0xbfb8aa3b, v5
	v_exp_f32_e32 v24, v24
	v_mul_f32_e32 v25, 0xbfb8aa3b, v25
	v_exp_f32_e32 v21, v21
	v_mul_f32_e32 v22, 0xbfb8aa3b, v23
	v_exp_f32_e32 v5, v5
	v_rcp_f32_e32 v194, v0
	v_add_f32_e32 v0, 1.0, v1
	v_mul_f32_e32 v1, 0xbfb8aa3b, v10
	v_exp_f32_e32 v25, v25
	v_exp_f32_e32 v22, v22
	v_rcp_f32_e32 v206, v0
	v_add_f32_e32 v0, 1.0, v2
	v_exp_f32_e32 v1, v1
	v_mul_f32_e32 v2, 0xbfb8aa3b, v11
	v_exp_f32_e32 v2, v2
	v_add_f32_e32 v4, 1.0, v4
	v_add_f32_e32 v24, 1.0, v24
	v_rcp_f32_e32 v191, v20
	v_add_f32_e32 v20, 1.0, v21
	v_rcp_f32_e32 v202, v4
	v_add_f32_e32 v4, 1.0, v5
	v_mul_f32_e32 v5, 0xbfb8aa3b, v6
	v_rcp_f32_e32 v185, v24
	v_add_f32_e32 v24, 1.0, v25
	v_mul_f32_e32 v25, 0xbfb8aa3b, v26
	v_rcp_f32_e32 v176, v20
	v_add_f32_e32 v20, 1.0, v22
	v_exp_f32_e32 v5, v5
	v_mul_f32_e32 v6, 0xbfb8aa3b, v7
	v_rcp_f32_e32 v207, v0
	v_add_f32_e32 v0, 1.0, v1
	s_cmp_eq_u32 s52, 1
	v_exp_f32_e32 v25, v25
	v_mul_f32_e32 v26, 0xbfb8aa3b, v27
	v_rcp_f32_e32 v178, v20
	v_exp_f32_e32 v6, v6
	v_rcp_f32_e32 v196, v0
	v_add_f32_e32 v0, 1.0, v2
	v_mov_b32_e32 v20, v198
	v_exp_f32_e32 v26, v26
	v_rcp_f32_e32 v197, v0
	s_cselect_b32 s12, s34, 0x1200
	s_cmp_lg_u32 s52, 0
	v_mul_f32_e32 v12, 0xbfb8aa3b, v12
	v_ashrrev_i32_e32 v21, 6, v20
	v_bfe_u32 v0, v20, 3, 3
	s_cselect_b32 s12, s12, 0x600
	v_lshl_or_b32 v0, v21, 3, v0
	v_mul_f32_e32 v16, 0xbfb8aa3b, v16
	v_exp_f32_e32 v12, v12
	v_mul_f32_e32 v13, 0xbfb8aa3b, v13
	v_rcp_f32_e32 v203, v4
	v_add_f32_e32 v4, 1.0, v5
	s_lshl_b32 s53, s12, 1
	v_lshrrev_b32_e32 v23, 1, v0
	v_rcp_f32_e32 v187, v24
	v_add_f32_e32 v24, 1.0, v25
	v_exp_f32_e32 v16, v16
	v_mul_f32_e32 v17, 0xbfb8aa3b, v17
	v_exp_f32_e32 v13, v13
	v_rcp_f32_e32 v188, v4
	v_add_f32_e32 v4, 1.0, v6
	s_add_u32 s12, s38, s53
	v_xor_b32_e32 v6, v23, v20
	v_rcp_f32_e32 v172, v24
	v_add_f32_e32 v24, 1.0, v26
	v_exp_f32_e32 v17, v17
	s_addc_u32 s13, s39, 0
	v_lshlrev_b32_e32 v6, 4, v6
	v_rcp_f32_e32 v174, v24
	v_mov_b64_e32 v[2:3], s[12:13]
	v_and_b32_e32 v64, 0x70, v6
	v_add_u32_e32 v6, 64, v0
	v_add_u32_e32 v24, 0x80, v0
	v_add_u32_e32 v25, 0xc0, v0
	v_add_f32_e32 v12, 1.0, v12
	v_rcp_f32_e32 v190, v4
	v_mad_i64_i32 v[4:5], s[12:13], v0, s35, v[2:3]
	v_mad_i64_i32 v[8:9], s[12:13], v6, s35, v[2:3]
	v_mad_i64_i32 v[10:11], s[12:13], v24, s35, v[2:3]
	v_mad_i64_i32 v[2:3], s[12:13], v25, s35, v[2:3]
	v_lshl_add_u32 v208, v21, 10, 0
	v_add_f32_e32 v16, 1.0, v16
	v_rcp_f32_e32 v200, v12
	v_add_f32_e32 v12, 1.0, v13
	v_mul_f32_e32 v13, 0xbfb8aa3b, v14
	v_readfirstlane_b32 s12, v208
	v_rcp_f32_e32 v193, v16
	v_add_f32_e32 v16, 1.0, v17
	v_mul_f32_e32 v17, 0xbfb8aa3b, v18
	v_exp_f32_e32 v13, v13
	v_mul_f32_e32 v14, 0xbfb8aa3b, v15
	v_lshl_add_u64 v[4:5], v[4:5], 0, v[64:65]
	s_mov_b32 m0, s12
	v_exp_f32_e32 v17, v17
	v_mul_f32_e32 v18, 0xbfb8aa3b, v19
	v_exp_f32_e32 v14, v14
	global_load_lds_dwordx4 v[4:5], off
	v_add_u32_e32 v4, 0x2000, v208
	v_exp_f32_e32 v18, v18
	v_readfirstlane_b32 s12, v4
	v_add_u32_e32 v4, 0x4000, v208
	v_lshl_add_u64 v[8:9], v[8:9], 0, v[64:65]
	s_mov_b32 m0, s12
	v_readfirstlane_b32 s12, v4
	v_add_u32_e32 v4, 0x6000, v208
	v_rcp_f32_e32 v201, v12
	v_add_f32_e32 v12, 1.0, v13
	s_lshl_b32 s54, s52, 20
	v_lshl_add_u64 v[10:11], v[10:11], 0, v[64:65]
	global_load_lds_dwordx4 v[8:9], off
	s_mov_b32 m0, s12
	v_readfirstlane_b32 s12, v4
	v_rcp_f32_e32 v195, v16
	v_add_f32_e32 v16, 1.0, v17
	v_rcp_f32_e32 v184, v12
	v_add_f32_e32 v12, 1.0, v14
	s_add_u32 s54, s40, s54
	v_ashrrev_i32_e32 v1, 31, v0
	v_lshl_add_u64 v[2:3], v[2:3], 0, v[64:65]
	global_load_lds_dwordx4 v[10:11], off
	s_mov_b32 m0, s12
	v_rcp_f32_e32 v180, v16
	v_add_f32_e32 v16, 1.0, v18
	v_rcp_f32_e32 v186, v12
	s_addc_u32 s55, s41, 0
	v_ashrrev_i32_e32 v7, 31, v6
	v_lshlrev_b64 v[12:13], 10, v[0:1]
	global_load_lds_dwordx4 v[2:3], off
	v_add_u32_e32 v2, 0x8000, v208
	v_rcp_f32_e32 v182, v16
	v_lshl_add_u64 v[14:15], s[54:55], 0, v[12:13]
	v_lshlrev_b64 v[16:17], 10, v[6:7]
	v_readfirstlane_b32 s12, v2
	v_add_u32_e32 v2, 0xa000, v208
	v_lshl_add_u64 v[14:15], v[14:15], 0, v[64:65]
	v_lshl_add_u64 v[18:19], s[54:55], 0, v[16:17]
	s_mov_b32 m0, s12
	v_readfirstlane_b32 s12, v2
	v_lshl_add_u64 v[18:19], v[18:19], 0, v[64:65]
	global_load_lds_dwordx4 v[14:15], off
	s_mov_b32 m0, s12
	v_mul_f32_e32 v60, 0xbfb8aa3b, v60
	global_load_lds_dwordx4 v[18:19], off
	v_mul_f32_e32 v56, 0xbfb8aa3b, v56
	v_mul_f32_e32 v52, 0xbfb8aa3b, v52
	v_mul_f32_e32 v48, 0xbfb8aa3b, v48
	v_mul_f32_e32 v44, 0xbfb8aa3b, v44
	v_mul_f32_e32 v40, 0xbfb8aa3b, v40
	v_mul_f32_e32 v36, 0xbfb8aa3b, v36
	v_mul_f32_e32 v32, 0xbfb8aa3b, v32
	v_mul_f32_e32 v28, 0xbfb8aa3b, v28
	v_exp_f32_e32 v60, v60
	v_mul_f32_e32 v61, 0xbfb8aa3b, v61
	v_exp_f32_e32 v56, v56
	v_mul_f32_e32 v57, 0xbfb8aa3b, v57
	v_exp_f32_e32 v52, v52
	v_mul_f32_e32 v53, 0xbfb8aa3b, v53
	v_exp_f32_e32 v48, v48
	v_mul_f32_e32 v49, 0xbfb8aa3b, v49
	v_exp_f32_e32 v44, v44
	v_mul_f32_e32 v45, 0xbfb8aa3b, v45
	v_exp_f32_e32 v40, v40
	v_mul_f32_e32 v41, 0xbfb8aa3b, v41
	v_exp_f32_e32 v36, v36
	v_mul_f32_e32 v37, 0xbfb8aa3b, v37
	v_exp_f32_e32 v32, v32
	v_mul_f32_e32 v33, 0xbfb8aa3b, v33
	v_exp_f32_e32 v28, v28
	v_mul_f32_e32 v29, 0xbfb8aa3b, v29
	v_exp_f32_e32 v61, v61
	v_exp_f32_e32 v57, v57
	v_exp_f32_e32 v53, v53
	v_exp_f32_e32 v49, v49
	v_exp_f32_e32 v45, v45
	v_exp_f32_e32 v41, v41
	v_exp_f32_e32 v37, v37
	v_exp_f32_e32 v33, v33
	v_exp_f32_e32 v29, v29
	v_lshrrev_b32_e32 v2, 31, v20
	v_add_u32_e32 v2, v21, v2
	v_add_f32_e32 v60, 1.0, v60
	v_add_f32_e32 v56, 1.0, v56
	v_add_f32_e32 v52, 1.0, v52
	v_add_f32_e32 v48, 1.0, v48
	v_add_f32_e32 v44, 1.0, v44
	v_add_f32_e32 v40, 1.0, v40
	v_add_f32_e32 v36, 1.0, v36
	v_add_f32_e32 v32, 1.0, v32
	v_add_f32_e32 v28, 1.0, v28
	v_bfe_u32 v1, v20, 4, 2
	v_bfe_u32 v7, v20, 1, 3
	v_and_b32_e32 v3, 0x7fffe, v2
	v_lshlrev_b32_e32 v2, 12, v2
	v_rcp_f32_e32 v149, v60
	v_add_f32_e32 v60, 1.0, v61
	v_mul_f32_e32 v61, 0xbfb8aa3b, v62
	v_rcp_f32_e32 v153, v56
	v_add_f32_e32 v56, 1.0, v57
	v_mul_f32_e32 v57, 0xbfb8aa3b, v58
	v_rcp_f32_e32 v157, v52
	v_add_f32_e32 v52, 1.0, v53
	v_mul_f32_e32 v53, 0xbfb8aa3b, v54
	v_rcp_f32_e32 v161, v48
	v_add_f32_e32 v48, 1.0, v49
	v_mul_f32_e32 v49, 0xbfb8aa3b, v50
	v_rcp_f32_e32 v165, v44
	v_add_f32_e32 v44, 1.0, v45
	v_mul_f32_e32 v45, 0xbfb8aa3b, v46
	v_rcp_f32_e32 v169, v40
	v_add_f32_e32 v40, 1.0, v41
	v_mul_f32_e32 v41, 0xbfb8aa3b, v42
	v_rcp_f32_e32 v173, v36
	v_add_f32_e32 v36, 1.0, v37
	v_mul_f32_e32 v37, 0xbfb8aa3b, v38
	v_rcp_f32_e32 v177, v32
	v_add_f32_e32 v32, 1.0, v33
	v_mul_f32_e32 v33, 0xbfb8aa3b, v34
	v_rcp_f32_e32 v181, v28
	v_add_f32_e32 v28, 1.0, v29
	v_mul_f32_e32 v29, 0xbfb8aa3b, v30
	v_and_b32_e32 v211, 0xffffe000, v2
	v_xor_b32_e32 v2, v1, v7
	v_bitop3_b32 v1, v1, v7, 4 bitop3:0x36
	v_exp_f32_e32 v61, v61
	v_mul_f32_e32 v62, 0xbfb8aa3b, v63
	v_exp_f32_e32 v57, v57
	v_mul_f32_e32 v58, 0xbfb8aa3b, v59
	v_exp_f32_e32 v53, v53
	v_mul_f32_e32 v54, 0xbfb8aa3b, v55
	v_exp_f32_e32 v49, v49
	v_mul_f32_e32 v50, 0xbfb8aa3b, v51
	v_exp_f32_e32 v45, v45
	v_mul_f32_e32 v46, 0xbfb8aa3b, v47
	v_exp_f32_e32 v41, v41
	v_mul_f32_e32 v42, 0xbfb8aa3b, v43
	v_exp_f32_e32 v37, v37
	v_mul_f32_e32 v38, 0xbfb8aa3b, v39
	v_exp_f32_e32 v33, v33
	v_mul_f32_e32 v34, 0xbfb8aa3b, v35
	v_exp_f32_e32 v29, v29
	v_mul_f32_e32 v30, 0xbfb8aa3b, v31
	v_lshlrev_b32_e32 v213, 4, v1
	v_bitop3_b32 v1, v23, 7, v20 bitop3:0x48
	v_exp_f32_e32 v62, v62
	v_exp_f32_e32 v58, v58
	v_exp_f32_e32 v54, v54
	v_exp_f32_e32 v50, v50
	v_exp_f32_e32 v46, v46
	v_exp_f32_e32 v42, v42
	v_exp_f32_e32 v38, v38
	v_exp_f32_e32 v34, v34
	v_exp_f32_e32 v30, v30
	v_lshlrev_b32_e32 v64, 4, v1
	v_mad_i64_i32 v[0:1], s[12:13], v0, s35, v[64:65]
	s_add_u32 s12, s42, s53
	v_rcp_f32_e32 v151, v60
	v_add_f32_e32 v60, 1.0, v61
	v_rcp_f32_e32 v155, v56
	v_add_f32_e32 v56, 1.0, v57
	v_rcp_f32_e32 v159, v52
	v_add_f32_e32 v52, 1.0, v53
	v_rcp_f32_e32 v163, v48
	v_add_f32_e32 v48, 1.0, v49
	v_rcp_f32_e32 v167, v44
	v_add_f32_e32 v44, 1.0, v45
	v_rcp_f32_e32 v171, v40
	v_add_f32_e32 v40, 1.0, v41
	v_rcp_f32_e32 v175, v36
	v_add_f32_e32 v36, 1.0, v37
	v_rcp_f32_e32 v179, v32
	v_add_f32_e32 v32, 1.0, v33
	v_rcp_f32_e32 v183, v28
	v_add_f32_e32 v28, 1.0, v29
	s_addc_u32 s13, s43, 0
	v_rcp_f32_e32 v142, v60
	v_add_f32_e32 v60, 1.0, v62
	v_rcp_f32_e32 v144, v56
	v_add_f32_e32 v56, 1.0, v58
	v_rcp_f32_e32 v146, v52
	v_add_f32_e32 v52, 1.0, v54
	v_rcp_f32_e32 v148, v48
	v_add_f32_e32 v48, 1.0, v50
	v_rcp_f32_e32 v152, v44
	v_add_f32_e32 v44, 1.0, v46
	v_rcp_f32_e32 v156, v40
	v_add_f32_e32 v40, 1.0, v42
	v_rcp_f32_e32 v160, v36
	v_add_f32_e32 v36, 1.0, v38
	v_rcp_f32_e32 v164, v32
	v_add_f32_e32 v32, 1.0, v34
	v_rcp_f32_e32 v168, v28
	v_add_f32_e32 v28, 1.0, v30
	v_lshl_add_u64 v[130:131], s[12:13], 0, v[0:1]
	v_mad_i64_i32 v[0:1], s[54:55], v6, s35, v[64:65]
	v_rcp_f32_e32 v143, v60
	v_rcp_f32_e32 v145, v56
	v_rcp_f32_e32 v147, v52
	v_rcp_f32_e32 v150, v48
	v_rcp_f32_e32 v154, v44
	v_rcp_f32_e32 v158, v40
	v_rcp_f32_e32 v162, v36
	v_rcp_f32_e32 v166, v32
	v_rcp_f32_e32 v170, v28
	v_lshl_add_u64 v[132:133], s[12:13], 0, v[0:1]
	v_mad_i64_i32 v[0:1], s[54:55], v24, s35, v[64:65]
	s_waitcnt vmcnt(0)
	v_lshl_add_u64 v[134:135], s[12:13], 0, v[0:1]
	v_mad_i64_i32 v[0:1], s[54:55], v25, s35, v[64:65]
	v_and_b32_e32 v22, 15, v20
	v_sub_u32_e32 v3, v21, v3
	v_lshl_add_u64 v[136:137], s[12:13], 0, v[0:1]
	v_or_b32_e32 v12, v12, v64
	v_or_b32_e32 v16, v16, v64
	v_mov_b32_e32 v0, 0
	s_mov_b32 s3, 0
	v_lshlrev_b32_e32 v209, 13, v3
	v_lshlrev_b32_e32 v210, 7, v22
	v_lshlrev_b32_e32 v212, 4, v2
	v_lshl_add_u64 v[138:139], s[4:5], 0, v[12:13]
	v_lshl_add_u64 v[140:141], s[4:5], 0, v[16:17]
	s_mov_b64 s[12:13], 0
	v_mov_b32_e32 v1, v0
	v_mov_b32_e32 v2, v0
	v_mov_b32_e32 v3, v0
	v_mov_b32_e32 v4, v0
	v_mov_b32_e32 v5, v0
	v_mov_b32_e32 v6, v0
	v_mov_b32_e32 v7, v0
	v_mov_b32_e32 v8, v0
	v_mov_b32_e32 v9, v0
	v_mov_b32_e32 v10, v0
	v_mov_b32_e32 v11, v0
	v_mov_b32_e32 v12, v0
	v_mov_b32_e32 v13, v0
	v_mov_b32_e32 v14, v0
	v_mov_b32_e32 v15, v0
	v_mov_b32_e32 v16, v0
	v_mov_b32_e32 v17, v0
	v_mov_b32_e32 v18, v0
	v_mov_b32_e32 v19, v0
	v_mov_b32_e32 v20, v0
	v_mov_b32_e32 v21, v0
	v_mov_b32_e32 v22, v0
	v_mov_b32_e32 v23, v0
	v_mov_b32_e32 v24, v0
	v_mov_b32_e32 v25, v0
	v_mov_b32_e32 v26, v0
	v_mov_b32_e32 v27, v0
	v_mov_b32_e32 v28, v0
	v_mov_b32_e32 v29, v0
	v_mov_b32_e32 v30, v0
	v_mov_b32_e32 v31, v0
	v_mov_b32_e32 v32, v0
	v_mov_b32_e32 v33, v0
	v_mov_b32_e32 v34, v0
	v_mov_b32_e32 v35, v0
	v_mov_b32_e32 v36, v0
	v_mov_b32_e32 v37, v0
	v_mov_b32_e32 v38, v0
	v_mov_b32_e32 v39, v0
	v_mov_b32_e32 v40, v0
	v_mov_b32_e32 v41, v0
	v_mov_b32_e32 v42, v0
	v_mov_b32_e32 v43, v0
	v_mov_b32_e32 v44, v0
	v_mov_b32_e32 v45, v0
	v_mov_b32_e32 v46, v0
	v_mov_b32_e32 v47, v0
	v_mov_b32_e32 v48, v0
	v_mov_b32_e32 v49, v0
	v_mov_b32_e32 v50, v0
	v_mov_b32_e32 v51, v0
	v_mov_b32_e32 v52, v0
	v_mov_b32_e32 v53, v0
	v_mov_b32_e32 v54, v0
	v_mov_b32_e32 v55, v0
	v_mov_b32_e32 v56, v0
	v_mov_b32_e32 v57, v0
	v_mov_b32_e32 v58, v0
	v_mov_b32_e32 v59, v0
	v_mov_b32_e32 v60, v0
	v_mov_b32_e32 v61, v0
	v_mov_b32_e32 v62, v0
	v_mov_b32_e32 v63, v0
	v_readfirstlane_b32 s54, v208
	s_nop 1
	s_add_i32 s54, s54, 0xc000
	s_mov_b32 m0, s54
	s_nop 0
	global_load_lds_dwordx4 v[130:131], off
	s_add_i32 m0, s54, 0x2000
	s_nop 0
	global_load_lds_dwordx4 v[132:133], off
	s_add_i32 m0, s54, 0x4000
	s_nop 0
	global_load_lds_dwordx4 v[134:135], off
	s_add_i32 m0, s54, 0x6000
	s_nop 0
	global_load_lds_dwordx4 v[136:137], off
	s_add_i32 m0, s54, 0x8000
	s_nop 0
	global_load_lds_dwordx4 v[138:139], off
	s_add_i32 m0, s54, 0xa000
	s_nop 0
	global_load_lds_dwordx4 v[140:141], off
	s_waitcnt vmcnt(6) lgkmcnt(0)
	s_barrier
	s_branch .LBB0_738
.LBB0_737:
	v_readfirstlane_b32 s54, v208
	s_add_i32 m0, s53, 2
	s_cmp_ge_u32 m0, 3
	s_cbranch_scc0 .Lg3a_gemm6
	s_sub_u32 m0, m0, 3
.Lg3a_gemm6:
	s_mul_i32 m0, m0, 0xc000
	s_add_i32 s54, s54, m0
	s_mul_i32 s53, s53, 0xc000
	s_add_i32 s53, s53, 0
	v_add3_u32 v64, s53, v209, v210
	v_add_u32_e32 v234, v64, v212
	v_add3_u32 v238, s53, v211, v210
	v_add_u32_e32 v239, v238, v212
	ds_read_b128 v[214:217], v234 offset:32768
	ds_read_b128 v[218:221], v234 offset:34816
	ds_read_b128 v[230:233], v234 offset:36864
	ds_read_b128 v[234:237], v234 offset:38912
	ds_read_b128 v[222:225], v239
	ds_read_b128 v[226:229], v239 offset:2048
	ds_read_b128 v[242:245], v239 offset:4096
	ds_read_b128 v[246:249], v239 offset:6144
	s_add_u32 s12, s12, 0x80
	s_addc_u32 s13, s13, 0
	s_mov_b32 m0, s54
	v_lshl_add_u64 v[254:255], v[130:131], 0, s[12:13]
	global_load_lds_dwordx4 v[254:255], off
	s_add_i32 m0, s54, 0x2000
	v_lshl_add_u64 v[254:255], v[132:133], 0, s[12:13]
	global_load_lds_dwordx4 v[254:255], off
	s_waitcnt lgkmcnt(2)
	v_mfma_f32_16x16x32_bf16 v[60:63], v[214:217], v[222:225], v[60:63]
	v_add_u32_e32 v64, v64, v213
	v_add_u32_e32 v238, v238, v213
	v_mfma_f32_16x16x32_bf16 v[44:47], v[214:217], v[226:229], v[44:47]
	v_mfma_f32_16x16x32_bf16 v[56:59], v[218:221], v[222:225], v[56:59]
	v_mfma_f32_16x16x32_bf16 v[40:43], v[218:221], v[226:229], v[40:43]
	s_add_i32 m0, s54, 0x4000
	v_lshl_add_u64 v[254:255], v[134:135], 0, s[12:13]
	global_load_lds_dwordx4 v[254:255], off
	v_mfma_f32_16x16x32_bf16 v[52:55], v[230:233], v[222:225], v[52:55]
	v_mfma_f32_16x16x32_bf16 v[36:39], v[230:233], v[226:229], v[36:39]
	v_mfma_f32_16x16x32_bf16 v[48:51], v[234:237], v[222:225], v[48:51]
	v_mfma_f32_16x16x32_bf16 v[32:35], v[234:237], v[226:229], v[32:35]
	s_add_i32 m0, s54, 0x6000
	v_lshl_add_u64 v[254:255], v[136:137], 0, s[12:13]
	global_load_lds_dwordx4 v[254:255], off
	ds_read_b128 v[222:225], v238
	ds_read_b128 v[226:229], v238 offset:2048
	s_waitcnt lgkmcnt(2)
	v_mfma_f32_16x16x32_bf16 v[28:31], v[214:217], v[242:245], v[28:31]
	v_mfma_f32_16x16x32_bf16 v[12:15], v[214:217], v[246:249], v[12:15]
	ds_read_b128 v[214:217], v64 offset:32768
	v_mfma_f32_16x16x32_bf16 v[24:27], v[218:221], v[242:245], v[24:27]
	v_mfma_f32_16x16x32_bf16 v[8:11], v[218:221], v[246:249], v[8:11]
	s_add_i32 m0, s54, 0x8000
	v_lshl_add_u64 v[254:255], v[138:139], 0, s[12:13]
	global_load_lds_dwordx4 v[254:255], off
	ds_read_b128 v[218:221], v64 offset:34816
	v_mfma_f32_16x16x32_bf16 v[20:23], v[230:233], v[242:245], v[20:23]
	v_mfma_f32_16x16x32_bf16 v[4:7], v[230:233], v[246:249], v[4:7]
	ds_read_b128 v[230:233], v64 offset:36864
	v_mfma_f32_16x16x32_bf16 v[16:19], v[234:237], v[242:245], v[16:19]
	v_mfma_f32_16x16x32_bf16 v[0:3], v[234:237], v[246:249], v[0:3]
	s_add_i32 m0, s54, 0xa000
	v_lshl_add_u64 v[254:255], v[140:141], 0, s[12:13]
	global_load_lds_dwordx4 v[254:255], off
	s_add_i32 s3, s3, 1
	s_cmpk_lg_i32 s12, 0x400
	ds_read_b128 v[234:237], v64 offset:38912
	ds_read_b128 v[242:245], v238 offset:4096
	ds_read_b128 v[246:249], v238 offset:6144
	s_waitcnt lgkmcnt(2)
	v_mfma_f32_16x16x32_bf16 v[60:63], v[214:217], v[222:225], v[60:63]
	v_mfma_f32_16x16x32_bf16 v[44:47], v[214:217], v[226:229], v[44:47]
	v_mfma_f32_16x16x32_bf16 v[56:59], v[218:221], v[222:225], v[56:59]
	v_mfma_f32_16x16x32_bf16 v[40:43], v[218:221], v[226:229], v[40:43]
	v_mfma_f32_16x16x32_bf16 v[52:55], v[230:233], v[222:225], v[52:55]
	v_mfma_f32_16x16x32_bf16 v[36:39], v[230:233], v[226:229], v[36:39]
	v_mfma_f32_16x16x32_bf16 v[48:51], v[234:237], v[222:225], v[48:51]
	v_mfma_f32_16x16x32_bf16 v[32:35], v[234:237], v[226:229], v[32:35]
	s_cbranch_scc0 .Lg3l_gemm6
	s_waitcnt vmcnt(6) lgkmcnt(0)
	s_branch .Lg3j_gemm6

.Lg3j_gemm6:
	v_mfma_f32_16x16x32_bf16 v[28:31], v[214:217], v[242:245], v[28:31]
	s_barrier
	v_mfma_f32_16x16x32_bf16 v[12:15], v[214:217], v[246:249], v[12:15]
	v_mfma_f32_16x16x32_bf16 v[24:27], v[218:221], v[242:245], v[24:27]
	v_mfma_f32_16x16x32_bf16 v[8:11], v[218:221], v[246:249], v[8:11]
	v_mfma_f32_16x16x32_bf16 v[20:23], v[230:233], v[242:245], v[20:23]
	v_mfma_f32_16x16x32_bf16 v[4:7], v[230:233], v[246:249], v[4:7]
	v_mfma_f32_16x16x32_bf16 v[16:19], v[234:237], v[242:245], v[16:19]
	v_mfma_f32_16x16x32_bf16 v[0:3], v[234:237], v[246:249], v[0:3]
	s_cbranch_scc0 .LBB0_731
.LBB0_738:
	s_mul_hi_u32 s53, s3, 0x55555556
	s_mul_i32 s53, s53, 3
	s_sub_u32 s53, s3, s53
	s_branch .LBB0_737
.LBB0_740:
	s_waitcnt vmcnt(0)
	s_nop 0
	v_mov_b32_e32 v0, v198
	s_barrier
	s_nop 0
	v_cmp_eq_u32_e32 vcc, 0, v0
	s_and_saveexec_b64 s[2:3], vcc
	s_cbranch_execz .LBB0_760
	s_mov_b64 s[4:5], exec
	buffer_wbl2 sc1
	s_waitcnt vmcnt(0)
	s_waitcnt vmcnt(0)
	v_mbcnt_lo_u32_b32 v0, s4, 0
	v_mbcnt_hi_u32_b32 v0, s5, v0
	v_cmp_eq_u32_e32 vcc, 0, v0
	s_and_saveexec_b64 s[6:7], vcc
	s_cbranch_execz .LBB0_743
	s_bcnt1_i32_b64 s0, s[4:5]
	v_mov_b32_e32 v1, 0
	v_mov_b32_e32 v2, s0
	global_atomic_add v1, v1, v2, s[56:57] offset:256 sc0

.LBB0_1502:
	s_nop 5
	v_mul_f32_e32 v0, 0xbfb8aa3b, v0
	v_exp_f32_e32 v0, v0
	v_mul_f32_e32 v1, 0xbfb8aa3b, v1
	v_exp_f32_e32 v1, v1
	v_mul_f32_e32 v20, 0xbfb8aa3b, v20
	v_add_f32_e32 v0, 1.0, v0
	v_rcp_f32_e32 v204, v0
	v_add_f32_e32 v0, 1.0, v1
	v_mul_f32_e32 v1, 0xbfb8aa3b, v2
	v_exp_f32_e32 v1, v1
	v_mul_f32_e32 v2, 0xbfb8aa3b, v3
	v_exp_f32_e32 v2, v2
	v_exp_f32_e32 v20, v20
	v_mul_f32_e32 v21, 0xbfb8aa3b, v21
	v_exp_f32_e32 v21, v21
	v_rcp_f32_e32 v205, v0
	v_add_f32_e32 v0, 1.0, v1
	v_mul_f32_e32 v1, 0xbfb8aa3b, v8
	v_rcp_f32_e32 v192, v0
	v_add_f32_e32 v0, 1.0, v2
	v_exp_f32_e32 v1, v1
	v_mul_f32_e32 v2, 0xbfb8aa3b, v9
	v_exp_f32_e32 v2, v2
	v_add_f32_e32 v20, 1.0, v20
	v_mul_f32_e32 v4, 0xbfb8aa3b, v4
	v_mul_f32_e32 v24, 0xbfb8aa3b, v24
	v_rcp_f32_e32 v189, v20
	v_add_f32_e32 v20, 1.0, v21
	v_mul_f32_e32 v21, 0xbfb8aa3b, v22
	v_exp_f32_e32 v4, v4
	v_mul_f32_e32 v5, 0xbfb8aa3b, v5
	v_exp_f32_e32 v24, v24
	v_mul_f32_e32 v25, 0xbfb8aa3b, v25
	v_exp_f32_e32 v21, v21
	v_mul_f32_e32 v22, 0xbfb8aa3b, v23
	v_exp_f32_e32 v5, v5
	v_rcp_f32_e32 v194, v0
	v_add_f32_e32 v0, 1.0, v1
	v_mul_f32_e32 v1, 0xbfb8aa3b, v10
	v_exp_f32_e32 v25, v25
	v_exp_f32_e32 v22, v22
	v_rcp_f32_e32 v206, v0
	v_add_f32_e32 v0, 1.0, v2
	v_exp_f32_e32 v1, v1
	v_mul_f32_e32 v2, 0xbfb8aa3b, v11
	v_exp_f32_e32 v2, v2
	v_add_f32_e32 v4, 1.0, v4
	v_add_f32_e32 v24, 1.0, v24
	v_rcp_f32_e32 v191, v20
	v_add_f32_e32 v20, 1.0, v21
	v_rcp_f32_e32 v202, v4
	v_add_f32_e32 v4, 1.0, v5
	v_mul_f32_e32 v5, 0xbfb8aa3b, v6
	v_rcp_f32_e32 v185, v24
	v_add_f32_e32 v24, 1.0, v25
	v_mul_f32_e32 v25, 0xbfb8aa3b, v26
	v_rcp_f32_e32 v176, v20
	v_add_f32_e32 v20, 1.0, v22
	v_exp_f32_e32 v5, v5
	v_mul_f32_e32 v6, 0xbfb8aa3b, v7
	v_rcp_f32_e32 v207, v0
	v_add_f32_e32 v0, 1.0, v1
	s_cmp_eq_u32 s44, 1
	v_exp_f32_e32 v25, v25
	v_mul_f32_e32 v26, 0xbfb8aa3b, v27
	v_rcp_f32_e32 v178, v20
	v_exp_f32_e32 v6, v6
	v_rcp_f32_e32 v196, v0
	v_add_f32_e32 v0, 1.0, v2
	v_mov_b32_e32 v20, v198
	v_exp_f32_e32 v26, v26
	v_rcp_f32_e32 v197, v0
	s_cselect_b32 s12, s34, 0x1200
	s_cmp_lg_u32 s44, 0
	v_mul_f32_e32 v12, 0xbfb8aa3b, v12
	v_ashrrev_i32_e32 v21, 6, v20
	v_bfe_u32 v0, v20, 3, 3
	s_cselect_b32 s12, s12, 0x600
	v_lshl_or_b32 v0, v21, 3, v0
	v_mul_f32_e32 v16, 0xbfb8aa3b, v16
	v_exp_f32_e32 v12, v12
	v_mul_f32_e32 v13, 0xbfb8aa3b, v13
	v_rcp_f32_e32 v203, v4
	v_add_f32_e32 v4, 1.0, v5
	s_lshl_b32 s45, s12, 1
	v_lshrrev_b32_e32 v23, 1, v0
	v_rcp_f32_e32 v187, v24
	v_add_f32_e32 v24, 1.0, v25
	v_exp_f32_e32 v16, v16
	v_mul_f32_e32 v17, 0xbfb8aa3b, v17
	v_exp_f32_e32 v13, v13
	v_rcp_f32_e32 v188, v4
	v_add_f32_e32 v4, 1.0, v6
	s_add_u32 s12, s38, s45
	v_xor_b32_e32 v6, v23, v20
	v_rcp_f32_e32 v172, v24
	v_add_f32_e32 v24, 1.0, v26
	v_exp_f32_e32 v17, v17
	s_addc_u32 s13, s39, 0
	v_lshlrev_b32_e32 v6, 4, v6
	v_rcp_f32_e32 v174, v24
	v_mov_b64_e32 v[2:3], s[12:13]
	v_and_b32_e32 v64, 0x70, v6
	v_add_u32_e32 v6, 64, v0
	v_add_u32_e32 v24, 0x80, v0
	v_add_u32_e32 v25, 0xc0, v0
	v_add_f32_e32 v12, 1.0, v12
	v_rcp_f32_e32 v190, v4
	v_mad_i64_i32 v[4:5], s[12:13], v0, s35, v[2:3]
	v_mad_i64_i32 v[8:9], s[12:13], v6, s35, v[2:3]
	v_mad_i64_i32 v[10:11], s[12:13], v24, s35, v[2:3]
	v_mad_i64_i32 v[2:3], s[12:13], v25, s35, v[2:3]
	v_lshl_add_u32 v208, v21, 10, 0
	v_add_f32_e32 v16, 1.0, v16
	v_rcp_f32_e32 v200, v12
	v_add_f32_e32 v12, 1.0, v13
	v_mul_f32_e32 v13, 0xbfb8aa3b, v14
	v_readfirstlane_b32 s12, v208
	v_rcp_f32_e32 v193, v16
	v_add_f32_e32 v16, 1.0, v17
	v_mul_f32_e32 v17, 0xbfb8aa3b, v18
	v_exp_f32_e32 v13, v13
	v_mul_f32_e32 v14, 0xbfb8aa3b, v15
	v_lshl_add_u64 v[4:5], v[4:5], 0, v[64:65]
	s_mov_b32 m0, s12
	v_exp_f32_e32 v17, v17
	v_mul_f32_e32 v18, 0xbfb8aa3b, v19
	v_exp_f32_e32 v14, v14
	global_load_lds_dwordx4 v[4:5], off
	v_add_u32_e32 v4, 0x2000, v208
	v_exp_f32_e32 v18, v18
	v_readfirstlane_b32 s12, v4
	v_add_u32_e32 v4, 0x4000, v208
	v_lshl_add_u64 v[8:9], v[8:9], 0, v[64:65]
	s_mov_b32 m0, s12
	v_readfirstlane_b32 s12, v4
	v_add_u32_e32 v4, 0x6000, v208
	v_rcp_f32_e32 v201, v12
	v_add_f32_e32 v12, 1.0, v13
	s_lshl_b32 s46, s44, 20
	v_lshl_add_u64 v[10:11], v[10:11], 0, v[64:65]
	global_load_lds_dwordx4 v[8:9], off
	s_mov_b32 m0, s12
	v_readfirstlane_b32 s12, v4
	v_rcp_f32_e32 v195, v16
	v_add_f32_e32 v16, 1.0, v17
	v_rcp_f32_e32 v184, v12
	v_add_f32_e32 v12, 1.0, v14
	s_add_u32 s46, s40, s46
	v_ashrrev_i32_e32 v1, 31, v0
	v_lshl_add_u64 v[2:3], v[2:3], 0, v[64:65]
	global_load_lds_dwordx4 v[10:11], off
	s_mov_b32 m0, s12
	v_rcp_f32_e32 v180, v16
	v_add_f32_e32 v16, 1.0, v18
	v_rcp_f32_e32 v186, v12
	s_addc_u32 s47, s41, 0
	v_ashrrev_i32_e32 v7, 31, v6
	v_lshlrev_b64 v[12:13], 10, v[0:1]
	global_load_lds_dwordx4 v[2:3], off
	v_add_u32_e32 v2, 0x8000, v208
	v_rcp_f32_e32 v182, v16
	v_lshl_add_u64 v[14:15], s[46:47], 0, v[12:13]
	v_lshlrev_b64 v[16:17], 10, v[6:7]
	v_readfirstlane_b32 s12, v2
	v_add_u32_e32 v2, 0xa000, v208
	v_lshl_add_u64 v[14:15], v[14:15], 0, v[64:65]
	v_lshl_add_u64 v[18:19], s[46:47], 0, v[16:17]
	s_mov_b32 m0, s12
	v_readfirstlane_b32 s12, v2
	v_lshl_add_u64 v[18:19], v[18:19], 0, v[64:65]
	global_load_lds_dwordx4 v[14:15], off
	s_mov_b32 m0, s12
	v_mul_f32_e32 v60, 0xbfb8aa3b, v60
	global_load_lds_dwordx4 v[18:19], off
	v_mul_f32_e32 v56, 0xbfb8aa3b, v56
	v_mul_f32_e32 v52, 0xbfb8aa3b, v52
	v_mul_f32_e32 v48, 0xbfb8aa3b, v48
	v_mul_f32_e32 v44, 0xbfb8aa3b, v44
	v_mul_f32_e32 v40, 0xbfb8aa3b, v40
	v_mul_f32_e32 v36, 0xbfb8aa3b, v36
	v_mul_f32_e32 v32, 0xbfb8aa3b, v32
	v_mul_f32_e32 v28, 0xbfb8aa3b, v28
	v_exp_f32_e32 v60, v60
	v_mul_f32_e32 v61, 0xbfb8aa3b, v61
	v_exp_f32_e32 v56, v56
	v_mul_f32_e32 v57, 0xbfb8aa3b, v57
	v_exp_f32_e32 v52, v52
	v_mul_f32_e32 v53, 0xbfb8aa3b, v53
	v_exp_f32_e32 v48, v48
	v_mul_f32_e32 v49, 0xbfb8aa3b, v49
	v_exp_f32_e32 v44, v44
	v_mul_f32_e32 v45, 0xbfb8aa3b, v45
	v_exp_f32_e32 v40, v40
	v_mul_f32_e32 v41, 0xbfb8aa3b, v41
	v_exp_f32_e32 v36, v36
	v_mul_f32_e32 v37, 0xbfb8aa3b, v37
	v_exp_f32_e32 v32, v32
	v_mul_f32_e32 v33, 0xbfb8aa3b, v33
	v_exp_f32_e32 v28, v28
	v_mul_f32_e32 v29, 0xbfb8aa3b, v29
	v_exp_f32_e32 v61, v61
	v_exp_f32_e32 v57, v57
	v_exp_f32_e32 v53, v53
	v_exp_f32_e32 v49, v49
	v_exp_f32_e32 v45, v45
	v_exp_f32_e32 v41, v41
	v_exp_f32_e32 v37, v37
	v_exp_f32_e32 v33, v33
	v_exp_f32_e32 v29, v29
	v_lshrrev_b32_e32 v2, 31, v20
	v_add_u32_e32 v2, v21, v2
	v_add_f32_e32 v60, 1.0, v60
	v_add_f32_e32 v56, 1.0, v56
	v_add_f32_e32 v52, 1.0, v52
	v_add_f32_e32 v48, 1.0, v48
	v_add_f32_e32 v44, 1.0, v44
	v_add_f32_e32 v40, 1.0, v40
	v_add_f32_e32 v36, 1.0, v36
	v_add_f32_e32 v32, 1.0, v32
	v_add_f32_e32 v28, 1.0, v28
	v_bfe_u32 v1, v20, 4, 2
	v_bfe_u32 v7, v20, 1, 3
	v_and_b32_e32 v3, 0x7fffe, v2
	v_lshlrev_b32_e32 v2, 12, v2
	v_rcp_f32_e32 v149, v60
	v_add_f32_e32 v60, 1.0, v61
	v_mul_f32_e32 v61, 0xbfb8aa3b, v62
	v_rcp_f32_e32 v153, v56
	v_add_f32_e32 v56, 1.0, v57
	v_mul_f32_e32 v57, 0xbfb8aa3b, v58
	v_rcp_f32_e32 v157, v52
	v_add_f32_e32 v52, 1.0, v53
	v_mul_f32_e32 v53, 0xbfb8aa3b, v54
	v_rcp_f32_e32 v161, v48
	v_add_f32_e32 v48, 1.0, v49
	v_mul_f32_e32 v49, 0xbfb8aa3b, v50
	v_rcp_f32_e32 v165, v44
	v_add_f32_e32 v44, 1.0, v45
	v_mul_f32_e32 v45, 0xbfb8aa3b, v46
	v_rcp_f32_e32 v169, v40
	v_add_f32_e32 v40, 1.0, v41
	v_mul_f32_e32 v41, 0xbfb8aa3b, v42
	v_rcp_f32_e32 v173, v36
	v_add_f32_e32 v36, 1.0, v37
	v_mul_f32_e32 v37, 0xbfb8aa3b, v38
	v_rcp_f32_e32 v177, v32
	v_add_f32_e32 v32, 1.0, v33
	v_mul_f32_e32 v33, 0xbfb8aa3b, v34
	v_rcp_f32_e32 v181, v28
	v_add_f32_e32 v28, 1.0, v29
	v_mul_f32_e32 v29, 0xbfb8aa3b, v30
	v_and_b32_e32 v211, 0xffffe000, v2
	v_xor_b32_e32 v2, v1, v7
	v_bitop3_b32 v1, v1, v7, 4 bitop3:0x36
	v_exp_f32_e32 v61, v61
	v_mul_f32_e32 v62, 0xbfb8aa3b, v63
	v_exp_f32_e32 v57, v57
	v_mul_f32_e32 v58, 0xbfb8aa3b, v59
	v_exp_f32_e32 v53, v53
	v_mul_f32_e32 v54, 0xbfb8aa3b, v55
	v_exp_f32_e32 v49, v49
	v_mul_f32_e32 v50, 0xbfb8aa3b, v51
	v_exp_f32_e32 v45, v45
	v_mul_f32_e32 v46, 0xbfb8aa3b, v47
	v_exp_f32_e32 v41, v41
	v_mul_f32_e32 v42, 0xbfb8aa3b, v43
	v_exp_f32_e32 v37, v37
	v_mul_f32_e32 v38, 0xbfb8aa3b, v39
	v_exp_f32_e32 v33, v33
	v_mul_f32_e32 v34, 0xbfb8aa3b, v35
	v_exp_f32_e32 v29, v29
	v_mul_f32_e32 v30, 0xbfb8aa3b, v31
	v_lshlrev_b32_e32 v213, 4, v1
	v_bitop3_b32 v1, v23, 7, v20 bitop3:0x48
	v_exp_f32_e32 v62, v62
	v_exp_f32_e32 v58, v58
	v_exp_f32_e32 v54, v54
	v_exp_f32_e32 v50, v50
	v_exp_f32_e32 v46, v46
	v_exp_f32_e32 v42, v42
	v_exp_f32_e32 v38, v38
	v_exp_f32_e32 v34, v34
	v_exp_f32_e32 v30, v30
	v_lshlrev_b32_e32 v64, 4, v1
	v_mad_i64_i32 v[0:1], s[12:13], v0, s35, v[64:65]
	s_add_u32 s12, s42, s45
	v_rcp_f32_e32 v151, v60
	v_add_f32_e32 v60, 1.0, v61
	v_rcp_f32_e32 v155, v56
	v_add_f32_e32 v56, 1.0, v57
	v_rcp_f32_e32 v159, v52
	v_add_f32_e32 v52, 1.0, v53
	v_rcp_f32_e32 v163, v48
	v_add_f32_e32 v48, 1.0, v49
	v_rcp_f32_e32 v167, v44
	v_add_f32_e32 v44, 1.0, v45
	v_rcp_f32_e32 v171, v40
	v_add_f32_e32 v40, 1.0, v41
	v_rcp_f32_e32 v175, v36
	v_add_f32_e32 v36, 1.0, v37
	v_rcp_f32_e32 v179, v32
	v_add_f32_e32 v32, 1.0, v33
	v_rcp_f32_e32 v183, v28
	v_add_f32_e32 v28, 1.0, v29
	s_addc_u32 s13, s43, 0
	v_rcp_f32_e32 v142, v60
	v_add_f32_e32 v60, 1.0, v62
	v_rcp_f32_e32 v144, v56
	v_add_f32_e32 v56, 1.0, v58
	v_rcp_f32_e32 v146, v52
	v_add_f32_e32 v52, 1.0, v54
	v_rcp_f32_e32 v148, v48
	v_add_f32_e32 v48, 1.0, v50
	v_rcp_f32_e32 v152, v44
	v_add_f32_e32 v44, 1.0, v46
	v_rcp_f32_e32 v156, v40
	v_add_f32_e32 v40, 1.0, v42
	v_rcp_f32_e32 v160, v36
	v_add_f32_e32 v36, 1.0, v38
	v_rcp_f32_e32 v164, v32
	v_add_f32_e32 v32, 1.0, v34
	v_rcp_f32_e32 v168, v28
	v_add_f32_e32 v28, 1.0, v30
	v_lshl_add_u64 v[130:131], s[12:13], 0, v[0:1]
	v_mad_i64_i32 v[0:1], s[46:47], v6, s35, v[64:65]
	v_rcp_f32_e32 v143, v60
	v_rcp_f32_e32 v145, v56
	v_rcp_f32_e32 v147, v52
	v_rcp_f32_e32 v150, v48
	v_rcp_f32_e32 v154, v44
	v_rcp_f32_e32 v158, v40
	v_rcp_f32_e32 v162, v36
	v_rcp_f32_e32 v166, v32
	v_rcp_f32_e32 v170, v28
	v_lshl_add_u64 v[132:133], s[12:13], 0, v[0:1]
	v_mad_i64_i32 v[0:1], s[46:47], v24, s35, v[64:65]
	s_waitcnt vmcnt(0)
	v_lshl_add_u64 v[134:135], s[12:13], 0, v[0:1]
	v_mad_i64_i32 v[0:1], s[46:47], v25, s35, v[64:65]
	v_and_b32_e32 v22, 15, v20
	v_sub_u32_e32 v3, v21, v3
	v_lshl_add_u64 v[136:137], s[12:13], 0, v[0:1]
	v_or_b32_e32 v12, v12, v64
	v_or_b32_e32 v16, v16, v64
	v_mov_b32_e32 v0, 0
	s_mov_b32 s3, 0
	v_lshlrev_b32_e32 v209, 13, v3
	v_lshlrev_b32_e32 v210, 7, v22
	v_lshlrev_b32_e32 v212, 4, v2
	v_lshl_add_u64 v[138:139], s[4:5], 0, v[12:13]
	v_lshl_add_u64 v[140:141], s[4:5], 0, v[16:17]
	s_mov_b64 s[12:13], 0
	v_mov_b32_e32 v1, v0
	v_mov_b32_e32 v2, v0
	v_mov_b32_e32 v3, v0
	v_mov_b32_e32 v4, v0
	v_mov_b32_e32 v5, v0
	v_mov_b32_e32 v6, v0
	v_mov_b32_e32 v7, v0
	v_mov_b32_e32 v8, v0
	v_mov_b32_e32 v9, v0
	v_mov_b32_e32 v10, v0
	v_mov_b32_e32 v11, v0
	v_mov_b32_e32 v12, v0
	v_mov_b32_e32 v13, v0
	v_mov_b32_e32 v14, v0
	v_mov_b32_e32 v15, v0
	v_mov_b32_e32 v16, v0
	v_mov_b32_e32 v17, v0
	v_mov_b32_e32 v18, v0
	v_mov_b32_e32 v19, v0
	v_mov_b32_e32 v20, v0
	v_mov_b32_e32 v21, v0
	v_mov_b32_e32 v22, v0
	v_mov_b32_e32 v23, v0
	v_mov_b32_e32 v24, v0
	v_mov_b32_e32 v25, v0
	v_mov_b32_e32 v26, v0
	v_mov_b32_e32 v27, v0
	v_mov_b32_e32 v28, v0
	v_mov_b32_e32 v29, v0
	v_mov_b32_e32 v30, v0
	v_mov_b32_e32 v31, v0
	v_mov_b32_e32 v32, v0
	v_mov_b32_e32 v33, v0
	v_mov_b32_e32 v34, v0
	v_mov_b32_e32 v35, v0
	v_mov_b32_e32 v36, v0
	v_mov_b32_e32 v37, v0
	v_mov_b32_e32 v38, v0
	v_mov_b32_e32 v39, v0
	v_mov_b32_e32 v40, v0
	v_mov_b32_e32 v41, v0
	v_mov_b32_e32 v42, v0
	v_mov_b32_e32 v43, v0
	v_mov_b32_e32 v44, v0
	v_mov_b32_e32 v45, v0
	v_mov_b32_e32 v46, v0
	v_mov_b32_e32 v47, v0
	v_mov_b32_e32 v48, v0
	v_mov_b32_e32 v49, v0
	v_mov_b32_e32 v50, v0
	v_mov_b32_e32 v51, v0
	v_mov_b32_e32 v52, v0
	v_mov_b32_e32 v53, v0
	v_mov_b32_e32 v54, v0
	v_mov_b32_e32 v55, v0
	v_mov_b32_e32 v56, v0
	v_mov_b32_e32 v57, v0
	v_mov_b32_e32 v58, v0
	v_mov_b32_e32 v59, v0
	v_mov_b32_e32 v60, v0
	v_mov_b32_e32 v61, v0
	v_mov_b32_e32 v62, v0
	v_mov_b32_e32 v63, v0
	v_readfirstlane_b32 s46, v208
	s_nop 1
	s_add_i32 s46, s46, 0xc000
	s_mov_b32 m0, s46
	s_nop 0
	global_load_lds_dwordx4 v[130:131], off
	s_add_i32 m0, s46, 0x2000
	s_nop 0
	global_load_lds_dwordx4 v[132:133], off
	s_add_i32 m0, s46, 0x4000
	s_nop 0
	global_load_lds_dwordx4 v[134:135], off
	s_add_i32 m0, s46, 0x6000
	s_nop 0
	global_load_lds_dwordx4 v[136:137], off
	s_add_i32 m0, s46, 0x8000
	s_nop 0
	global_load_lds_dwordx4 v[138:139], off
	s_add_i32 m0, s46, 0xa000
	s_nop 0
	global_load_lds_dwordx4 v[140:141], off
	s_waitcnt vmcnt(6) lgkmcnt(0)
	s_barrier
	s_branch .LBB0_1504
.LBB0_1503:
	v_readfirstlane_b32 s46, v208
	s_add_i32 m0, s45, 2
	s_cmp_ge_u32 m0, 3
	s_cbranch_scc0 .Lg3a_gemm1
	s_sub_u32 m0, m0, 3
.Lg3a_gemm1:
	s_mul_i32 m0, m0, 0xc000
	s_add_i32 s46, s46, m0
	s_mul_i32 s45, s45, 0xc000
	s_add_i32 s45, s45, 0
	v_add3_u32 v64, s45, v209, v210
	v_add_u32_e32 v234, v64, v212
	v_add3_u32 v238, s45, v211, v210
	v_add_u32_e32 v239, v238, v212
	ds_read_b128 v[214:217], v234 offset:32768
	ds_read_b128 v[218:221], v234 offset:34816
	ds_read_b128 v[230:233], v234 offset:36864
	ds_read_b128 v[234:237], v234 offset:38912
	ds_read_b128 v[222:225], v239
	ds_read_b128 v[226:229], v239 offset:2048
	ds_read_b128 v[242:245], v239 offset:4096
	ds_read_b128 v[246:249], v239 offset:6144
	s_add_u32 s12, s12, 0x80
	s_addc_u32 s13, s13, 0
	s_mov_b32 m0, s46
	v_lshl_add_u64 v[254:255], v[130:131], 0, s[12:13]
	global_load_lds_dwordx4 v[254:255], off
	s_add_i32 m0, s46, 0x2000
	v_lshl_add_u64 v[254:255], v[132:133], 0, s[12:13]
	global_load_lds_dwordx4 v[254:255], off
	s_waitcnt lgkmcnt(2)
	v_mfma_f32_16x16x32_bf16 v[60:63], v[214:217], v[222:225], v[60:63]
	v_add_u32_e32 v64, v64, v213
	v_add_u32_e32 v238, v238, v213
	v_mfma_f32_16x16x32_bf16 v[44:47], v[214:217], v[226:229], v[44:47]
	v_mfma_f32_16x16x32_bf16 v[56:59], v[218:221], v[222:225], v[56:59]
	v_mfma_f32_16x16x32_bf16 v[40:43], v[218:221], v[226:229], v[40:43]
	s_add_i32 m0, s46, 0x4000
	v_lshl_add_u64 v[254:255], v[134:135], 0, s[12:13]
	global_load_lds_dwordx4 v[254:255], off
	v_mfma_f32_16x16x32_bf16 v[52:55], v[230:233], v[222:225], v[52:55]
	v_mfma_f32_16x16x32_bf16 v[36:39], v[230:233], v[226:229], v[36:39]
	v_mfma_f32_16x16x32_bf16 v[48:51], v[234:237], v[222:225], v[48:51]
	v_mfma_f32_16x16x32_bf16 v[32:35], v[234:237], v[226:229], v[32:35]
	s_add_i32 m0, s46, 0x6000
	v_lshl_add_u64 v[254:255], v[136:137], 0, s[12:13]
	global_load_lds_dwordx4 v[254:255], off
	ds_read_b128 v[222:225], v238
	ds_read_b128 v[226:229], v238 offset:2048
	s_waitcnt lgkmcnt(2)
	v_mfma_f32_16x16x32_bf16 v[28:31], v[214:217], v[242:245], v[28:31]
	v_mfma_f32_16x16x32_bf16 v[12:15], v[214:217], v[246:249], v[12:15]
	ds_read_b128 v[214:217], v64 offset:32768
	v_mfma_f32_16x16x32_bf16 v[24:27], v[218:221], v[242:245], v[24:27]
	v_mfma_f32_16x16x32_bf16 v[8:11], v[218:221], v[246:249], v[8:11]
	s_add_i32 m0, s46, 0x8000
	v_lshl_add_u64 v[254:255], v[138:139], 0, s[12:13]
	global_load_lds_dwordx4 v[254:255], off
	ds_read_b128 v[218:221], v64 offset:34816
	v_mfma_f32_16x16x32_bf16 v[20:23], v[230:233], v[242:245], v[20:23]
	v_mfma_f32_16x16x32_bf16 v[4:7], v[230:233], v[246:249], v[4:7]
	ds_read_b128 v[230:233], v64 offset:36864
	v_mfma_f32_16x16x32_bf16 v[16:19], v[234:237], v[242:245], v[16:19]
	v_mfma_f32_16x16x32_bf16 v[0:3], v[234:237], v[246:249], v[0:3]
	s_add_i32 m0, s46, 0xa000
	v_lshl_add_u64 v[254:255], v[140:141], 0, s[12:13]
	global_load_lds_dwordx4 v[254:255], off
	s_add_i32 s3, s3, 1
	s_cmpk_lg_i32 s12, 0x400
	ds_read_b128 v[234:237], v64 offset:38912
	ds_read_b128 v[242:245], v238 offset:4096
	ds_read_b128 v[246:249], v238 offset:6144
	s_waitcnt lgkmcnt(2)
	v_mfma_f32_16x16x32_bf16 v[60:63], v[214:217], v[222:225], v[60:63]
	v_mfma_f32_16x16x32_bf16 v[44:47], v[214:217], v[226:229], v[44:47]
	v_mfma_f32_16x16x32_bf16 v[56:59], v[218:221], v[222:225], v[56:59]
	v_mfma_f32_16x16x32_bf16 v[40:43], v[218:221], v[226:229], v[40:43]
	v_mfma_f32_16x16x32_bf16 v[52:55], v[230:233], v[222:225], v[52:55]
	v_mfma_f32_16x16x32_bf16 v[36:39], v[230:233], v[226:229], v[36:39]
	v_mfma_f32_16x16x32_bf16 v[48:51], v[234:237], v[222:225], v[48:51]
	v_mfma_f32_16x16x32_bf16 v[32:35], v[234:237], v[226:229], v[32:35]
	s_cbranch_scc0 .Lg3l_gemm1
	s_waitcnt vmcnt(6) lgkmcnt(0)
	s_branch .Lg3j_gemm1

.LBB0_1504:
	s_mul_hi_u32 s45, s3, 0x55555556
	s_mul_i32 s45, s45, 3
	s_sub_u32 s45, s3, s45
	s_branch .LBB0_1503
.LBB0_1506:
	s_waitcnt vmcnt(0)
	s_nop 0
	v_mov_b32_e32 v0, v198
	s_barrier
	s_nop 0
	v_cmp_eq_u32_e32 vcc, 0, v0
	s_and_saveexec_b64 s[2:3], vcc
	s_cbranch_execz .LBB0_1526
	s_mov_b64 s[4:5], exec
	buffer_wbl2 sc1
	s_waitcnt vmcnt(0)
	s_waitcnt vmcnt(0)
	v_mbcnt_lo_u32_b32 v0, s4, 0
	v_mbcnt_hi_u32_b32 v0, s5, v0
	v_cmp_eq_u32_e32 vcc, 0, v0
	s_and_saveexec_b64 s[6:7], vcc
	s_cbranch_execz .LBB0_1509
	s_bcnt1_i32_b64 s0, s[4:5]
	v_mov_b32_e32 v1, 0
	v_mov_b32_e32 v2, s0
	global_atomic_add v1, v1, v2, s[56:57] offset:256 sc0
